# HGRN loops: second-read copies folded into their consumers, three s_nop pads replaced by the following counted waits
# speedup vs baseline: 1.0010x; 1.0010x over previous
; #define LAS __attribute__((address_space(3)))
; __device__ __forceinline__ unsigned cvt_pk_bf16(float lo, float hi) { unsigned r; asm volatile("v_cvt_pk_bf16_f32 %0, %1, %2" : "=v"(r) : "v"(lo), "v"(hi)); return r; }
; __device__ __forceinline__ float bf2f(unsigned short b) { return __uint_as_float(((unsigned)b) << 16); }
; template <bool FULL>
; __device__ __forceinline__ void hgrn_item(LAS unsigned char* lds, const bf16_t* P, bf16_t* AB, int L, int hd, const float* lbv, const float* anorm, const float* S0, const float* Dd, int ns, float* Sout, float* Dout) {
;     ...
;         float cs[4], kk[4], qv[4];
;         {
;             float run = 0.f;
; #pragma unroll
;             for (int i = 0; i < 4; ++i) { float z = bf2f(zc[i]); z = fminf(fmaxf(z, -30.f), 30.f); const float e = __expf(-z), sg = __builtin_amdgcn_rcpf(1.f + e), sn = e * sg;
;                 const float f = lb + oml * sg; run += __builtin_amdgcn_logf(f) * 0.69314718056f; cs[i] = run; kk[i] = oml * sn; qv[i] = bf2f(qc[i]); }
;             qsum[tq * 128 + k] = run;
;         }
;         __syncthreads();
;         {
;             float pre = 0.f, tot = 0.f;
; #pragma unroll
;             for (int j = 0; j < 4; ++j) { const float v = qsum[j * 128 + k]; tot += v; pre += (j < tq) ? v : 0.f; }
;             btot += tot;
;             float kh[4];
; #pragma unroll
;             for (int i = 0; i < 4; ++i) { const float b = pre + cs[i]; const float qt = qv[i] * __expf(b), kt = kk[i] * __expf(fminf(-b, 80.f)); kh[i] = kk[i] * __expf(tot - b);
;                 Qt[(4 * tq + i) * 136 + k] = (bf16_t)(cvt_pk_bf16(qt, 0.f) & 0xffffu); Kt[(4 * tq + i) * 136 + k] = (bf16_t)(cvt_pk_bf16(kt, 0.f) & 0xffffu); }
;             u32x2 kp; kp.x = cvt_pk_bf16(kh[0], kh[1]); kp.y = cvt_pk_bf16(kh[2], kh[3]);
;             *(LAS u32x2*)(KhT + k * 20 + 4 * tq) = kp;
;             if (tq == 0) dvec[k] = __expf(tot);
.LBB0_227:
	s_or_b64 exec, exec, s[4:5]
	v_lshlrev_b32_e32 v68, 16, v68
	v_max_f32_e32 v68, v68, v68
	v_med3_f32 v68, v68, s29, v225
	v_lshlrev_b32_e32 v72, 16, v72
	v_mul_f32_e32 v68, 0xbfb8aa3b, v68
	v_max_f32_e32 v72, v72, v72
	v_lshlrev_b32_e32 v70, 16, v70
	v_exp_f32_e32 v68, v68
	v_med3_f32 v72, v72, s29, v225
	v_max_f32_e32 v70, v70, v70
	v_mul_f32_e32 v72, 0xbfb8aa3b, v72
	v_med3_f32 v70, v70, s29, v225
	v_lshlrev_b32_e32 v47, 16, v47
	v_exp_f32_e32 v72, v72
	v_mul_f32_e32 v70, 0xbfb8aa3b, v70
	v_max_f32_e32 v47, v47, v47
	v_exp_f32_e32 v70, v70
	v_add_f32_e32 v69, 1.0, v68
	v_med3_f32 v47, v47, s29, v225
	v_rcp_f32_e32 v69, v69
	v_mul_f32_e32 v47, 0xbfb8aa3b, v47
	v_exp_f32_e32 v47, v47
	v_add_f32_e32 v73, 1.0, v72
	v_rcp_f32_e32 v73, v73
	v_add_f32_e32 v71, 1.0, v70
	v_rcp_f32_e32 v71, v71
	v_mul_f32_e32 v68, v68, v69
	v_mul_f32_e32 v78, v55, v68
	v_add_f32_e32 v68, 1.0, v47
	v_rcp_f32_e32 v68, v68
	v_mul_f32_e32 v72, v72, v73
	v_fma_f32 v73, v55, v73, v53
	v_log_f32_e32 v73, v73
	v_mul_f32_e32 v70, v70, v71
	v_fma_f32 v71, v55, v71, v53
	v_log_f32_e32 v71, v71
	v_fma_f32 v69, v55, v69, v53
	v_log_f32_e32 v69, v69
	v_mul_f32_e32 v47, v47, v68
	v_fma_f32 v68, v55, v68, v53
	v_log_f32_e32 v68, v68
	v_add_f32_e32 v75, v71, v73
	v_mul_f32_e32 v79, v55, v47
	v_add_f32_e32 v47, v69, v75
	v_add_f32_e32 v81, v68, v47
	ds_write_b32 v54, v81 offset:19456
	s_waitcnt lgkmcnt(0)
	s_barrier
	ds_read2st64_b32 v[68:69], v49 offset0:76 offset1:78
	ds_read2st64_b32 v[128:129], v49 offset0:80 offset1:82
	v_mul_f32_e32 v76, v55, v70
	v_mul_f32_e32 v72, v55, v72
	s_waitcnt lgkmcnt(1)
	v_add_f32_e32 v46, 0, v68
	v_cndmask_b32_e64 v68, 0, v46, s[46:47]
	v_add_f32_e32 v46, v46, v69
	v_cndmask_b32_e64 v69, 0, v69, s[44:45]
	v_add_f32_e32 v70, v68, v69
	s_waitcnt lgkmcnt(0)
	v_add_f32_e32 v46, v46, v128
	v_cndmask_b32_e64 v68, 0, v128, s[42:43]
	v_add_f32_e32 v68, v70, v68
	v_cndmask_b32_e64 v70, 0, v129, s[40:41]
	v_add_f32_e32 v71, v68, v70
	v_add_f32_e32 v68, v73, v71
	v_mov_b32_e32 v70, v129
	v_pk_add_f32 v[46:47], v[46:47], v[70:71]
	v_sub_f32_e32 v68, v46, v68
	v_exp_f32_e32 v68, v68
	v_add_f32_e32 v69, v75, v71
	v_mul_f32_e32 v68, v72, v68
	v_sub_f32_e32 v69, v46, v69
	v_exp_f32_e32 v69, v69
	v_sub_f32_e32 v47, v46, v47
	v_add_f32_e32 v67, v81, v71
	v_sub_f32_e32 v67, v46, v67
	v_exp_f32_e32 v47, v47
	v_exp_f32_e32 v67, v67
	v_mul_f32_e32 v69, v76, v69
	v_mul_f32_e32 v47, v78, v47
	v_mul_f32_e32 v67, v79, v67
	v_cvt_pk_bf16_f32 v68, v68, v69
	v_cvt_pk_bf16_f32 v69, v47, v67
	ds_write_b64 v52, v[68:69] offset:8704
	s_and_saveexec_b64 s[4:5], s[38:39]
	s_cbranch_execz .LBB0_229
	v_exp_f32_e32 v47, v46
	ds_write_b32 v49, v47 offset:18944

; template <bool FULL>
; __device__ __forceinline__ void hgrn_item(LAS unsigned char* lds, const bf16_t* P, bf16_t* AB, int L, int hd, const float* lbv, const float* anorm, const float* S0, const float* Dd, int ns, float* Sout, float* Dout) {
;     ...
;         __syncthreads();
;         f32x4 acco = (f32x4){0.f, 0.f, 0.f, 0.f};
;         {
;             const u32x2 vv = *(const LAS u32x2*)(VsT + (16 * w + c16) * 20 + 4 * q4);
;             const bf16x4 vf = __builtin_bit_cast(bf16x4, vv);
;             if (FULL) {
;             bf16x8 qf[4], kf[4];
; #pragma unroll
;             for (int kq = 0; kq < 4; ++kq) {
;                 const u32x2 a0 = *(const LAS u32x2*)(Qt + c16 * 136 + 32 * kq + 4 * q4), a1 = *(const LAS u32x2*)(Qt + c16 * 136 + 32 * kq + 16 + 4 * q4);
;                 const u32x2 b0 = *(const LAS u32x2*)(Kt + c16 * 136 + 32 * kq + 4 * q4), b1 = *(const LAS u32x2*)(Kt + c16 * 136 + 32 * kq + 16 + 4 * q4);
;                 u32x4 qa = (u32x4){a0.x, a0.y, a1.x, a1.y}, ka = (u32x4){b0.x, b0.y, b1.x, b1.y};
;                 qf[kq] = __builtin_bit_cast(bf16x8, qa); kf[kq] = __builtin_bit_cast(bf16x8, ka);
;             }
;             f32x4 accA = (f32x4){0.f, 0.f, 0.f, 0.f};
; #pragma unroll
;             for (int kq = 0; kq < 4; ++kq) accA = __builtin_amdgcn_mfma_f32_16x16x32_bf16(kf[kq], qf[kq], accA, 0, 0, 0);
; #pragma unroll
;             for (int j = 0; j < 4; ++j) accA[j] = (c16 >= 4 * q4 + j) ? accA[j] : 0.f;
;             u32x2 pa; pa.x = cvt_pk_bf16(accA[0], accA[1]); pa.y = cvt_pk_bf16(accA[2], accA[3]);
;             const bf16x4 pA = __builtin_bit_cast(bf16x4, pa);
;             acco = __builtin_amdgcn_mfma_f32_16x16x16bf16_1k(pA, vf, (f32x4){0.f, 0.f, 0.f, 0.f}, 0, 0, 0);
; #pragma unroll
;             for (int kq = 0; kq < 4; ++kq) {
;                 u32x4 sp; sp.x = cvt_pk_bf16(accS[2 * kq][0], accS[2 * kq][1]); sp.y = cvt_pk_bf16(accS[2 * kq][2], accS[2 * kq][3]);
;                 sp.z = cvt_pk_bf16(accS[2 * kq + 1][0], accS[2 * kq + 1][1]); sp.w = cvt_pk_bf16(accS[2 * kq + 1][2], accS[2 * kq + 1][3]);
;                 acco = __builtin_amdgcn_mfma_f32_16x16x32_bf16(qf[kq], __builtin_bit_cast(bf16x8, sp), acco, 0, 0, 0);
;             }
;             }
; #pragma unroll
;             for (int mt = 0; mt < 8; ++mt) {
;                 const u32x2 kh2 = *(const LAS u32x2*)(KhT + (16 * mt + c16) * 20 + 4 * q4);
.LBB0_231:
	s_or_b64 exec, exec, s[4:5]
	v_add_u32_e32 v38, v57, v56
	s_waitcnt lgkmcnt(0)
	s_barrier
	ds_read_b64 v[36:37], v50 offset:13824
	ds_read_b128 v[156:159], v38 offset:18944
	v_add_f32_e32 v48, v48, v46
	v_add_u32_e32 v46, 0x2000, v58
	ds_read2_b64 v[68:71], v46 offset0:64 offset1:144
	v_add_u32_e32 v39, 0x2400, v58
	v_add_u32_e32 v47, 0x2800, v58
	v_add_u32_e32 v67, 0x3000, v58
	ds_read_b128 v[160:163], v38 offset:19008
	ds_read_b128 v[164:167], v38 offset:19072
	ds_read_b128 v[168:171], v38 offset:19136
	ds_read2_b64 v[196:199], v39 offset0:96 offset1:176
	ds_read_b128 v[172:175], v38 offset:19200
	ds_read_b128 v[176:179], v38 offset:19264
	ds_read2_b64 v[200:203], v47 offset0:128 offset1:208
	ds_read_b128 v[180:183], v38 offset:19328
	ds_read_b128 v[184:187], v38 offset:19392
	ds_read2_b64 v[204:207], v67 offset0:32 offset1:112
	s_add_u32 s2, s2, 0x2c000
	s_addc_u32 s3, s3, 0
	s_cmp_eq_u32 s2, 0x554000
	s_waitcnt lgkmcnt(11)
	v_pk_mul_f32 v[28:29], v[28:29], v[156:157]
	v_pk_mul_f32 v[30:31], v[30:31], v[158:159]
	s_waitcnt lgkmcnt(9)
	v_pk_mul_f32 v[24:25], v[24:25], v[160:161]
	v_pk_mul_f32 v[26:27], v[26:27], v[162:163]
	v_mfma_f32_16x16x16_bf16 v[28:31], v[68:69], v[36:37], v[28:31]
	s_waitcnt lgkmcnt(6)
	v_mfma_f32_16x16x16_bf16 v[24:27], v[70:71], v[36:37], v[24:27]
	v_pk_mul_f32 v[20:21], v[20:21], v[164:165]
	v_pk_mul_f32 v[22:23], v[22:23], v[166:167]
	v_pk_mul_f32 v[16:17], v[16:17], v[168:169]
	v_pk_mul_f32 v[18:19], v[18:19], v[170:171]
	v_mfma_f32_16x16x16_bf16 v[20:23], v[196:197], v[36:37], v[20:23]
	s_waitcnt lgkmcnt(3)
	v_mfma_f32_16x16x16_bf16 v[16:19], v[198:199], v[36:37], v[16:19]
	v_pk_mul_f32 v[12:13], v[12:13], v[172:173]
	v_pk_mul_f32 v[14:15], v[14:15], v[174:175]
	v_pk_mul_f32 v[8:9], v[8:9], v[176:177]
	v_pk_mul_f32 v[10:11], v[10:11], v[178:179]
	v_mfma_f32_16x16x16_bf16 v[12:15], v[200:201], v[36:37], v[12:15]
	s_waitcnt lgkmcnt(0)
	v_mfma_f32_16x16x16_bf16 v[8:11], v[202:203], v[36:37], v[8:11]
	v_pk_mul_f32 v[4:5], v[4:5], v[180:181]
	v_pk_mul_f32 v[6:7], v[6:7], v[182:183]
	v_pk_mul_f32 v[0:1], v[0:1], v[184:185]
	v_pk_mul_f32 v[2:3], v[2:3], v[186:187]
	v_mfma_f32_16x16x16_bf16 v[4:7], v[204:205], v[36:37], v[4:7]
	s_nop 0
	v_mfma_f32_16x16x16_bf16 v[0:3], v[206:207], v[36:37], v[0:3]
	s_cbranch_scc1 .LBB0_233
	s_waitcnt vmcnt(0)
	v_mov_b64_e32 v[38:39], v[34:35]
	v_mov_b32_e32 v47, v61
	v_mov_b32_e32 v68, v63
	v_mov_b32_e32 v70, v64
	v_mov_b32_e32 v72, v66
	v_mov_b64_e32 v[36:37], v[32:33]
	s_branch .LBB0_225

; #define LAS __attribute__((address_space(3)))
; __device__ __forceinline__ unsigned cvt_pk_bf16(float lo, float hi) { unsigned r; asm volatile("v_cvt_pk_bf16_f32 %0, %1, %2" : "=v"(r) : "v"(lo), "v"(hi)); return r; }
; __device__ __forceinline__ float bf2f(unsigned short b) { return __uint_as_float(((unsigned)b) << 16); }
; template <bool FULL>
; __device__ __forceinline__ void hgrn_item(LAS unsigned char* lds, const bf16_t* P, bf16_t* AB, int L, int hd, const float* lbv, const float* anorm, const float* S0, const float* Dd, int ns, float* Sout, float* Dout) {
;     ...
;         float cs[4], kk[4], qv[4];
;         {
;             float run = 0.f;
; #pragma unroll
;             for (int i = 0; i < 4; ++i) { float z = bf2f(zc[i]); z = fminf(fmaxf(z, -30.f), 30.f); const float e = __expf(-z), sg = __builtin_amdgcn_rcpf(1.f + e), sn = e * sg;
;                 const float f = lb + oml * sg; run += __builtin_amdgcn_logf(f) * 0.69314718056f; cs[i] = run; kk[i] = oml * sn; qv[i] = bf2f(qc[i]); }
;             qsum[tq * 128 + k] = run;
;         }
;         __syncthreads();
;         {
;             float pre = 0.f, tot = 0.f;
; #pragma unroll
;             for (int j = 0; j < 4; ++j) { const float v = qsum[j * 128 + k]; tot += v; pre += (j < tq) ? v : 0.f; }
;             btot += tot;
;             float kh[4];
; #pragma unroll
;             for (int i = 0; i < 4; ++i) { const float b = pre + cs[i]; const float qt = qv[i] * __expf(b), kt = kk[i] * __expf(fminf(-b, 80.f)); kh[i] = kk[i] * __expf(tot - b);
;                 Qt[(4 * tq + i) * 136 + k] = (bf16_t)(cvt_pk_bf16(qt, 0.f) & 0xffffu); Kt[(4 * tq + i) * 136 + k] = (bf16_t)(cvt_pk_bf16(kt, 0.f) & 0xffffu); }
;             u32x2 kp; kp.x = cvt_pk_bf16(kh[0], kh[1]); kp.y = cvt_pk_bf16(kh[2], kh[3]);
;             *(LAS u32x2*)(KhT + k * 20 + 4 * tq) = kp;
;             if (tq == 0) dvec[k] = __expf(tot);
.LBB0_333:
	s_or_b64 exec, exec, s[0:1]
	v_lshlrev_b32_e32 v51, 16, v41
	v_lshlrev_b32_e32 v41, 16, v44
	v_max_f32_e32 v41, v41, v41
	v_med3_f32 v41, v41, s29, v225
	v_mul_f32_e32 v41, 0xbfb8aa3b, v41
	v_exp_f32_e32 v41, v41
	v_lshlrev_b32_e32 v47, 16, v47
	v_max_f32_e32 v47, v47, v47
	v_lshlrev_b32_e32 v45, 16, v45
	v_add_f32_e32 v44, 1.0, v41
	v_rcp_f32_e32 v44, v44
	v_med3_f32 v47, v47, s29, v225
	v_max_f32_e32 v45, v45, v45
	v_mul_f32_e32 v47, 0xbfb8aa3b, v47
	v_mul_f32_e32 v41, v41, v44
	v_med3_f32 v45, v45, s29, v225
	v_mul_f32_e32 v52, v89, v41
	v_lshlrev_b32_e32 v41, 16, v42
	v_exp_f32_e32 v47, v47
	v_mul_f32_e32 v45, 0xbfb8aa3b, v45
	v_max_f32_e32 v41, v41, v41
	v_exp_f32_e32 v45, v45
	v_med3_f32 v41, v41, s29, v225
	v_mul_f32_e32 v41, 0xbfb8aa3b, v41
	v_exp_f32_e32 v41, v41
	v_add_f32_e32 v48, 1.0, v47
	v_rcp_f32_e32 v48, v48
	v_add_f32_e32 v49, 1.0, v45
	v_rcp_f32_e32 v49, v49
	v_add_f32_e32 v42, 1.0, v41
	v_rcp_f32_e32 v42, v42
	v_mul_f32_e32 v47, v47, v48
	v_fma_f32 v48, v89, v48, v103
	v_log_f32_e32 v48, v48
	v_mul_f32_e32 v45, v45, v49
	v_fma_f32 v49, v89, v49, v103
	v_log_f32_e32 v49, v49
	v_fma_f32 v44, v89, v44, v103
	v_log_f32_e32 v44, v44
	v_mul_f32_e32 v41, v41, v42
	v_fma_f32 v42, v89, v42, v103
	v_log_f32_e32 v42, v42
	v_add_f32_e32 v49, v49, v48
	v_mul_f32_e32 v54, v89, v41
	v_add_f32_e32 v41, v44, v49
	v_add_f32_e32 v56, v42, v41
	v_lshlrev_b32_e32 v53, 16, v43
	ds_write_b32 v92, v56 offset:19456
	s_waitcnt lgkmcnt(0)
	s_barrier
	ds_read2st64_b32 v[42:43], v93 offset0:76 offset1:78
	ds_read2st64_b32 v[128:129], v93 offset0:80 offset1:82
	v_lshlrev_b32_e32 v55, 16, v40
	v_mul_f32_e32 v50, v89, v45
	v_lshlrev_b32_e32 v46, 16, v46
	v_mul_f32_e32 v47, v89, v47
	s_waitcnt lgkmcnt(1)
	v_add_f32_e32 v40, 0, v42
	v_cndmask_b32_e64 v42, 0, v40, s[40:41]
	v_add_f32_e32 v40, v40, v43
	v_cndmask_b32_e64 v43, 0, v43, s[42:43]
	v_add_f32_e32 v44, v42, v43
	s_waitcnt lgkmcnt(0)
	v_add_f32_e32 v40, v40, v128
	v_cndmask_b32_e64 v42, 0, v128, s[44:45]
	v_add_f32_e32 v42, v44, v42
	v_cndmask_b32_e64 v44, 0, v129, s[46:47]
	v_add_f32_e32 v45, v42, v44
	v_add_f32_e32 v42, v48, v45
	v_exp_f32_e32 v44, v42
	s_nop 0
	v_mul_f32_e32 v46, v44, v46
	v_min_f32_e64 v44, -v42, s99
	v_exp_f32_e32 v44, v44
	s_nop 0
	v_mul_f32_e32 v48, v47, v44
	v_mov_b32_e32 v44, v129
	v_cvt_pk_bf16_f32 v43, v46, v48
	ds_write_b16 v96, v43
	ds_write_b16_d16_hi v96, v43 offset:4352
	v_add_f32_e32 v43, v49, v45
	v_pk_add_f32 v[40:41], v[40:41], v[44:45]
	v_exp_f32_e32 v44, v43
	v_min_f32_e64 v46, -v43, s99
	v_exp_f32_e32 v46, v46
	v_mul_f32_e32 v44, v44, v51
	v_mul_f32_e32 v46, v50, v46
	v_cvt_pk_bf16_f32 v44, v44, v46
	ds_write_b16 v96, v44 offset:272
	ds_write_b16_d16_hi v96, v44 offset:4624
	v_exp_f32_e32 v44, v41
	v_min_f32_e64 v46, -v41, s99
	v_exp_f32_e32 v46, v46
	v_mul_f32_e32 v44, v44, v53
	v_mul_f32_e32 v46, v52, v46
	v_cvt_pk_bf16_f32 v44, v44, v46
	ds_write_b16 v96, v44 offset:544
	ds_write_b16_d16_hi v96, v44 offset:4896
	v_add_f32_e32 v44, v56, v45
	v_sub_f32_e32 v42, v40, v42
	v_sub_f32_e32 v43, v40, v43
	v_sub_f32_e32 v41, v40, v41
	v_exp_f32_e32 v45, v44
	v_min_f32_e64 v46, -v44, s99
	v_sub_f32_e32 v44, v40, v44
	v_exp_f32_e32 v42, v42
	v_exp_f32_e32 v43, v43
	v_exp_f32_e32 v41, v41
	v_exp_f32_e32 v46, v46
	v_exp_f32_e32 v44, v44
	v_mul_f32_e32 v45, v45, v55
	v_mul_f32_e32 v42, v47, v42
	v_mul_f32_e32 v43, v50, v43
	v_mul_f32_e32 v41, v52, v41
	v_mul_f32_e32 v46, v54, v46
	v_mul_f32_e32 v44, v54, v44
	v_cvt_pk_bf16_f32 v45, v45, v46
	ds_write_b16 v96, v45 offset:816
	ds_write_b16_d16_hi v96, v45 offset:5168
	v_cvt_pk_bf16_f32 v42, v42, v43
	v_cvt_pk_bf16_f32 v43, v41, v44
	ds_write_b64 v98, v[42:43] offset:8704
	s_and_saveexec_b64 s[0:1], s[36:37]
	s_cbranch_execz .LBB0_335
	v_exp_f32_e32 v40, v40
	ds_write_b32 v93, v40 offset:18944
